# stack + software-pipelined fast path for far key tiles in the MAIN attention loop (K frags of both 32-key tiles + V frags prefetched, tile-B QK and exp under tile-A PV); accumulator mapping fixed for
# speedup vs baseline: 1.0214x; 1.0214x over previous
; DI void attn_item(const Params& p, int g, int seq, int hd, int qt, int m, char* smem, int split_j, int sub) {
;     ...
;   auto compute = [&](int st, int buf) __attribute__((always_inline)) {
;     const int k0 = (tbase + st) * 32, h = h_, l31 = l31_;
;     const bf16_t* Kb = Ks + buf * 32 * 72; const bf16_t* Vb = Vs + buf * 128 * 40;
;     const int rmin = k0 - (qw0 + 31), rmax = k0 + 31 - qw0;
;     const bool farL = rmax <= -128, farR = rmin >= 128;
;     if (!farL && region == 0) { rescale(__builtin_amdgcn_exp2f(cneg)); region = 1; }
;     if (farR && region == 1) { rescale(__builtin_amdgcn_exp2f(-cpos)); region = 2; }
;     bf16x8 kf[4], vf[2][4];
; #pragma unroll
;     for (int s = 0; s < 4; ++s) kf[s] = *(const bf16x8*)(Kb + l31 * 72 + s * 16 + h * 8);
; #pragma unroll
;     for (int s2 = 0; s2 < 2; ++s2)
; #pragma unroll
;       for (int dt = 0; dt < 4; ++dt) vf[s2][dt] = *(const bf16x8*)(Vb + (dt * 32 + l31) * 40 + s2 * 16 + h * 8);
;     __builtin_amdgcn_sched_barrier(0);
;     f32x16 X;
; #pragma unroll
;     for (int r = 0; r < 16; ++r) X[r] = 0.f;
; #pragma unroll
;     for (int s = 0; s < 4; ++s) X = MFMA32(kf[s], qf[s], X);
;     if (farL || farR) {
; #pragma unroll
;       for (int r = 0; r < 16; ++r) X[r] = __builtin_amdgcn_exp2f(X[r]);
;     } else {
;       const int rel0 = k0 - (qw0 + l31) + 128;
; #pragma unroll
;       for (int r = 0; r < 16; ++r) { int idx = rel0 + crow(r, h); idx = idx < 0 ? 0 : (idx > 256 ? 256 : idx); X[r] = __builtin_amdgcn_exp2f(X[r] + tab[idx]); }
;     }
;     bf16x8 pf[2];
; #pragma unroll
;     for (int s2 = 0; s2 < 2; ++s2) {
;       u32x4 w; w.x = pk_bf16(X[8 * s2], X[8 * s2 + 1]); w.y = pk_bf16(X[8 * s2 + 2], X[8 * s2 + 3]); w.z = pk_bf16(X[8 * s2 + 4], X[8 * s2 + 5]); w.w = pk_bf16(X[8 * s2 + 6], X[8 * s2 + 7]);
;       ls2 += (f32x2){X[8 * s2], X[8 * s2 + 1]}; ls2 += (f32x2){X[8 * s2 + 2], X[8 * s2 + 3]};
;       ls2 += (f32x2){X[8 * s2 + 4], X[8 * s2 + 5]}; ls2 += (f32x2){X[8 * s2 + 6], X[8 * s2 + 7]};
;       pf[s2] = __builtin_bit_cast(bf16x8, w);
;     }
; #pragma unroll
;     for (int s2 = 0; s2 < 2; ++s2)
; #pragma unroll
;       for (int dt = 0; dt < 4; ++dt) O[dt] = MFMA32(pf[s2], vf[s2][dt], O[dt]);
;   };
;   load_tile(0, rkA, rvA0, rvA1);
;   load_tile(1, rkB, rvB0, rvB1);
;   __syncthreads();
;   store_tile(0, rkA, rvA0, rvA1);
;   store_tile(1, rkB, rvB0, rvB1);
;   __syncthreads();
.Lat2_fast:
	s_add_i32 s10, s6, -3
	s_and_b32 s16, s10, 2
	s_mul_i32 s10, s16, 0x1200
	s_mul_i32 s18, s16, 0x2800
	v_add_u32_e32 v192, s10, v191
	v_add_u32_e32 v244, s18, v196
	ds_read_b128 v[64:67], v192
	ds_read_b128 v[80:83], v192 offset:32
	ds_read_b128 v[84:87], v192 offset:64
	ds_read_b128 v[88:91], v192 offset:96
	ds_read_b128 v[220:223], v192 offset:4608
	ds_read_b128 v[224:227], v192 offset:4640
	ds_read_b128 v[236:239], v192 offset:4672
	ds_read_b128 v[240:243], v192 offset:4704
	ds_read_b128 v[156:159], v244 offset:18432
	ds_read_b128 v[160:163], v244 offset:20992
	ds_read_b128 v[164:167], v244 offset:23552
	ds_read_b128 v[152:155], v244 offset:26112
	s_waitcnt lgkmcnt(11)
	v_mfma_f32_32x32x16_bf16 v[64:79], v[64:67], v[104:107], 0
	s_waitcnt lgkmcnt(10)
	v_mfma_f32_32x32x16_bf16 v[64:79], v[80:83], v[108:111], v[64:79]
	s_waitcnt lgkmcnt(9)
	v_mfma_f32_32x32x16_bf16 v[64:79], v[84:87], v[112:115], v[64:79]
	s_waitcnt lgkmcnt(8)
	v_mfma_f32_32x32x16_bf16 v[64:79], v[88:91], v[116:119], v[64:79]
	ds_read_b128 v[148:151], v244 offset:18464
	ds_read_b128 v[144:147], v244 offset:21024
	ds_read_b128 v[136:139], v244 offset:23584
	ds_read_b128 v[140:143], v244 offset:26144
	s_waitcnt lgkmcnt(11)
	v_mfma_f32_32x32x16_bf16 v[80:95], v[220:223], v[104:107], 0
	s_waitcnt lgkmcnt(10)
	v_mfma_f32_32x32x16_bf16 v[80:95], v[224:227], v[108:111], v[80:95]
	s_waitcnt lgkmcnt(9)
	v_mfma_f32_32x32x16_bf16 v[80:95], v[236:239], v[112:115], v[80:95]
	s_waitcnt lgkmcnt(8)
	v_mfma_f32_32x32x16_bf16 v[80:95], v[240:243], v[116:119], v[80:95]
	s_nop 1
	v_exp_f32_e32 v64, v64
	v_exp_f32_e32 v65, v65
	v_exp_f32_e32 v66, v66
	v_exp_f32_e32 v67, v67
	v_exp_f32_e32 v68, v68
	v_exp_f32_e32 v69, v69
	v_exp_f32_e32 v70, v70
	v_exp_f32_e32 v71, v71
	v_exp_f32_e32 v72, v72
	v_exp_f32_e32 v73, v73
	v_exp_f32_e32 v74, v74
	v_exp_f32_e32 v75, v75
	v_exp_f32_e32 v76, v76
	v_exp_f32_e32 v77, v77
	v_exp_f32_e32 v78, v78
	v_exp_f32_e32 v79, v79
	v_pk_add_f32 v[246:247], v[66:67], v[70:71]
	v_pk_add_f32 v[186:187], v[186:187], v[64:65]
	v_pk_add_f32 v[246:247], v[246:247], v[74:75]
	v_pk_add_f32 v[186:187], v[186:187], v[68:69]
	v_pk_add_f32 v[246:247], v[246:247], v[78:79]
	v_pk_add_f32 v[186:187], v[186:187], v[72:73]
	v_pk_add_f32 v[186:187], v[186:187], v[76:77]
	v_pk_add_f32 v[186:187], v[186:187], v[246:247]
	v_cvt_pk_bf16_f32 v64, v64, v65
	v_cvt_pk_bf16_f32 v65, v66, v67
	v_cvt_pk_bf16_f32 v66, v68, v69
	v_cvt_pk_bf16_f32 v67, v70, v71
	v_cvt_pk_bf16_f32 v68, v72, v73
	v_cvt_pk_bf16_f32 v69, v74, v75
	v_cvt_pk_bf16_f32 v70, v76, v77
	v_cvt_pk_bf16_f32 v71, v78, v79
	s_waitcnt lgkmcnt(7)
	v_mfma_f32_32x32x16_bf16 v[48:63], v[64:67], v[156:159], v[48:63]
	ds_read_b128 v[156:159], v244 offset:28672
	v_exp_f32_e32 v80, v80
	v_exp_f32_e32 v81, v81
	v_exp_f32_e32 v82, v82
	s_waitcnt lgkmcnt(7)
	v_mfma_f32_32x32x16_bf16 v[32:47], v[64:67], v[160:163], v[32:47]
	ds_read_b128 v[160:163], v244 offset:31232
	v_exp_f32_e32 v83, v83
	v_exp_f32_e32 v84, v84
	v_exp_f32_e32 v85, v85
	s_waitcnt lgkmcnt(7)
	v_mfma_f32_32x32x16_bf16 v[16:31], v[64:67], v[164:167], v[16:31]
	ds_read_b128 v[164:167], v244 offset:33792
	v_exp_f32_e32 v86, v86
	v_exp_f32_e32 v87, v87
	v_exp_f32_e32 v88, v88
	s_waitcnt lgkmcnt(7)
	v_mfma_f32_32x32x16_bf16 v[0:15], v[64:67], v[152:155], v[0:15]
	ds_read_b128 v[152:155], v244 offset:36352
	v_exp_f32_e32 v89, v89
	v_exp_f32_e32 v90, v90
	v_exp_f32_e32 v91, v91
	s_waitcnt lgkmcnt(7)
	v_mfma_f32_32x32x16_bf16 v[48:63], v[68:71], v[148:151], v[48:63]
	ds_read_b128 v[148:151], v244 offset:28704
	v_exp_f32_e32 v92, v92
	v_exp_f32_e32 v93, v93
	v_exp_f32_e32 v94, v94
	v_exp_f32_e32 v95, v95
	s_waitcnt lgkmcnt(7)
	v_mfma_f32_32x32x16_bf16 v[32:47], v[68:71], v[144:147], v[32:47]
	ds_read_b128 v[144:147], v244 offset:31264
	v_pk_add_f32 v[246:247], v[82:83], v[86:87]
	v_pk_add_f32 v[186:187], v[186:187], v[80:81]
	v_pk_add_f32 v[246:247], v[246:247], v[90:91]
	v_pk_add_f32 v[186:187], v[186:187], v[84:85]
	s_waitcnt lgkmcnt(7)
	v_mfma_f32_32x32x16_bf16 v[16:31], v[68:71], v[136:139], v[16:31]
	ds_read_b128 v[136:139], v244 offset:33824
	v_pk_add_f32 v[246:247], v[246:247], v[94:95]
	v_pk_add_f32 v[186:187], v[186:187], v[88:89]
	v_pk_add_f32 v[186:187], v[186:187], v[92:93]
	v_pk_add_f32 v[186:187], v[186:187], v[246:247]
	s_waitcnt lgkmcnt(7)
	v_mfma_f32_32x32x16_bf16 v[0:15], v[68:71], v[140:143], v[0:15]
	ds_read_b128 v[140:143], v244 offset:36384
	v_cvt_pk_bf16_f32 v80, v80, v81
	v_cvt_pk_bf16_f32 v81, v82, v83
	v_cvt_pk_bf16_f32 v82, v84, v85
	v_cvt_pk_bf16_f32 v83, v86, v87
	v_cvt_pk_bf16_f32 v84, v88, v89
	v_cvt_pk_bf16_f32 v85, v90, v91
	v_cvt_pk_bf16_f32 v86, v92, v93
	v_cvt_pk_bf16_f32 v87, v94, v95
	s_waitcnt lgkmcnt(7)
	v_mfma_f32_32x32x16_bf16 v[48:63], v[80:83], v[156:159], v[48:63]
	s_waitcnt lgkmcnt(6)
	v_mfma_f32_32x32x16_bf16 v[32:47], v[80:83], v[160:163], v[32:47]
	s_waitcnt lgkmcnt(5)
	v_mfma_f32_32x32x16_bf16 v[16:31], v[80:83], v[164:167], v[16:31]
	s_waitcnt lgkmcnt(4)
	v_mfma_f32_32x32x16_bf16 v[0:15], v[80:83], v[152:155], v[0:15]
	s_waitcnt lgkmcnt(3)
	v_mfma_f32_32x32x16_bf16 v[48:63], v[84:87], v[148:151], v[48:63]
	s_waitcnt lgkmcnt(2)
	v_mfma_f32_32x32x16_bf16 v[32:47], v[84:87], v[144:147], v[32:47]
	s_waitcnt lgkmcnt(1)
	v_mfma_f32_32x32x16_bf16 v[16:31], v[84:87], v[136:139], v[16:31]
	s_waitcnt lgkmcnt(0)
	v_mfma_f32_32x32x16_bf16 v[0:15], v[84:87], v[140:143], v[0:15]
	s_andn2_b64 vcc, exec, s[8:9]
	s_cbranch_vccnz .Lat2_bot
	s_xor_b32 s7, s16, 2
	s_mul_i32 s8, s7, 0x2800
	s_add_i32 s8, s8, 32
	s_mulk_i32 s7, 0x1200
	v_add_u32_e32 v80, s7, v169
	v_add3_u32 v81, s8, v189, v190
	s_addk_i32 s8, 0x2800
	s_waitcnt vmcnt(5)
	ds_write_b128 v80, v[96:99]
	s_waitcnt vmcnt(4)
	ds_write_b128 v81, v[100:103] offset:18432
	s_waitcnt vmcnt(3)
	ds_write_b128 v81, v[120:123] offset:23552
	s_waitcnt vmcnt(2)
	ds_write_b128 v80, v[124:127] offset:4608
	v_add3_u32 v80, s8, v189, v190
	s_waitcnt vmcnt(1)
	ds_write_b128 v80, v[128:131] offset:18432
	s_waitcnt vmcnt(0)
	ds_write_b128 v80, v[132:135] offset:23552
.Lat2_bot:
	s_add_i32 s13, s13, 64
	s_add_i32 s6, s6, 2
	s_cmp_lg_u32 s73, s15
	s_waitcnt lgkmcnt(0)
	s_barrier
	s_cbranch_scc1 .LBB0_317
	s_branch .LBB0_337

; DI void attn_item(const Params& p, int g, int seq, int hd, int qt, int m, char* smem, int split_j, int sub) {
;     ...
;     const int k0 = (tbase + st) * 32, h = h_, l31 = l31_;
;     const bf16_t* Kb = Ks + buf * 32 * 72; const bf16_t* Vb = Vs + buf * 128 * 40;
;     const int rmin = k0 - (qw0 + 31), rmax = k0 + 31 - qw0;
;     const bool farL = rmax <= -128, farR = rmin >= 128;
;     if (!farL && region == 0) { rescale(__builtin_amdgcn_exp2f(cneg)); region = 1; }
;     if (farR && region == 1) { rescale(__builtin_amdgcn_exp2f(-cpos)); region = 2; }
;     ...
;   for (int it = 0; it < npairs; ++it) {
;     const int set = it & 1;
;     if (it + 1 < npairs) { load_tile(2 * it + 2, rkA, rvA0, rvA1); load_tile(2 * it + 3, rkB, rvB0, rvB1); }
;     compute(2 * it, 2 * set);
;     compute(2 * it + 1, 2 * set + 1);
.LBB0_319:
	s_add_i32 s7, s14, s13
	s_cmpk_lt_i32 s7, 0xff42
	s_cbranch_scc1 .Lat2_fast
	s_cmpk_gt_i32 s7, 0x9e
	s_cbranch_scc0 .Lat2_slow
	s_cmp_eq_u32 s17, 2
	s_cbranch_scc1 .Lat2_fast
.Lat2_slow:
	s_add_i32 s10, s7, 31
	s_cmpk_lt_i32 s10, 0xff81
	s_cselect_b64 s[10:11], -1, 0
	s_cmp_lg_u32 s17, 0
	s_cselect_b64 s[18:19], -1, 0
	s_or_b64 s[10:11], s[10:11], s[18:19]
	s_and_b64 vcc, exec, s[10:11]
	s_cbranch_vccnz .LBB0_321
	v_mov_b32_e32 v175, v174
	v_pk_mul_f32 v[62:63], v[174:175], v[62:63]
	v_pk_mul_f32 v[60:61], v[174:175], v[60:61]
	v_pk_mul_f32 v[58:59], v[174:175], v[58:59]
	v_pk_mul_f32 v[56:57], v[174:175], v[56:57]
	v_pk_mul_f32 v[54:55], v[174:175], v[54:55]
	v_pk_mul_f32 v[52:53], v[174:175], v[52:53]
	v_pk_mul_f32 v[50:51], v[174:175], v[50:51]
	v_pk_mul_f32 v[48:49], v[182:183], v[48:49]
	v_pk_mul_f32 v[46:47], v[174:175], v[46:47]
	v_pk_mul_f32 v[44:45], v[174:175], v[44:45]
	v_pk_mul_f32 v[42:43], v[174:175], v[42:43]
	v_pk_mul_f32 v[40:41], v[174:175], v[40:41]
	v_pk_mul_f32 v[38:39], v[174:175], v[38:39]
	v_pk_mul_f32 v[36:37], v[174:175], v[36:37]
	v_pk_mul_f32 v[34:35], v[174:175], v[34:35]
	v_pk_mul_f32 v[32:33], v[182:183], v[32:33]
	v_pk_mul_f32 v[30:31], v[174:175], v[30:31]
	v_pk_mul_f32 v[28:29], v[174:175], v[28:29]
	v_pk_mul_f32 v[26:27], v[174:175], v[26:27]
	v_pk_mul_f32 v[24:25], v[174:175], v[24:25]
	v_pk_mul_f32 v[22:23], v[174:175], v[22:23]
	v_pk_mul_f32 v[20:21], v[174:175], v[20:21]
	v_pk_mul_f32 v[18:19], v[174:175], v[18:19]
	v_pk_mul_f32 v[16:17], v[182:183], v[16:17]
	v_pk_mul_f32 v[14:15], v[174:175], v[14:15]
	v_pk_mul_f32 v[12:13], v[174:175], v[12:13]
	v_pk_mul_f32 v[10:11], v[174:175], v[10:11]
	v_pk_mul_f32 v[8:9], v[174:175], v[8:9]
	v_pk_mul_f32 v[6:7], v[174:175], v[6:7]
	v_pk_mul_f32 v[4:5], v[174:175], v[4:5]
	v_pk_mul_f32 v[2:3], v[174:175], v[2:3]
	v_pk_mul_f32 v[0:1], v[182:183], v[0:1]
	v_pk_mul_f32 v[186:187], v[178:179], v[186:187]
	s_mov_b32 s17, 1
